# w1/w2 conversion loops in the S5 phase: stores of an item stay in flight through the next item (early copy of the prefetched quarter moved behind the counted ladder, header drain removed), on top of D
# speedup vs baseline: 1.0061x; 1.0061x over previous
; #define LAS __attribute__((address_space(3)))
; #define GAS __attribute__((address_space(1)))
; __device__ __forceinline__ void tr_load(const TrItem& t, f32x4 (&v)[8], int lane) {
;     const int nblk = t.N / 32, kb = t.item / nblk, nb = t.item % nblk, k0 = 64 * kb, n0 = 32 * nb;
; #pragma unroll
;     for (int i = 0; i < 8; ++i) v[i] = __builtin_nontemporal_load((const GAS f32x4*)(t.W + (size_t)(k0 + 8 * i + (lane >> 3)) * t.N + n0 + 4 * (lane & 7)));
; }
; template <bool PB>
; __device__ __forceinline__ void phase_s5(const PView& p, int l, LAS unsigned char* lds, int lane, int wave) {
;     ...
;     TrPair tp; const bool conv_first = wave >= 4;
;     if (!PB) { const float* const in_I_W1 = p.in[I_W1]; const float* const in_I_W2 = p.in[I_W2];
;         tp.W0 = in_I_W1 + (size_t)l * DM * DFF; tp.T0 = (bf16_t*)(ws + WS_W1) + (size_t)l * DFF * DM; tp.s0 = nullptr; tp.K0 = DM; tp.N0 = DFF; tp.n0 = (DM / 64) * (DFF / 32);
;         tp.W1 = in_I_W2 + (size_t)l * DFF * DM; tp.T1 = (bf16_t*)(ws + WS_W2) + (size_t)l * DM * DFF; tp.s1 = nullptr; tp.K1 = DFF; tp.N1 = DM; tp.n1 = (DFF / 64) * (DM / 32);
;         if (conv_first) tr_run(tp, (LAS float*)(lds + wave * S5_STRIDE + 8704), gw, NGW, lane); }
.LBB0_338:
	s_andn2_b64 vcc, exec, s[0:1]
	s_cbranch_vccnz .LBB0_403
	s_add_i32 s0, s95, 0x23e70
	v_mov_b32_e32 v0, s0
	ds_read_b32 v0, v0
	s_add_i32 s0, s95, 0x23e74
	s_waitcnt lgkmcnt(0)
	v_mov_b32_e32 v0, s0
	ds_read_b32 v0, v0
	s_add_i32 s0, s95, 0x23e68
	s_waitcnt lgkmcnt(0)
	v_mov_b32_e32 v0, s0
	ds_read_b32 v0, v0
	s_add_i32 s0, s95, 0x23e6c
	s_waitcnt lgkmcnt(0)
	v_mov_b32_e32 v0, s0
	ds_read_b32 v0, v0
	s_add_i32 s0, s95, 0x23e60
	s_waitcnt lgkmcnt(0)
	v_mov_b32_e32 v0, s0
	ds_read_b32 v0, v0
	s_add_i32 s0, s95, 0x23e64
	s_waitcnt lgkmcnt(0)
	v_mov_b32_e32 v0, s0
	s_mul_i32 s0, s20, 0x4400
	s_add_i32 s22, s20, s73
	s_add_i32 s23, s95, s0
	s_cmp_gt_i32 s20, 3
	s_cselect_b64 s[14:15], -1, 0
	s_cmp_lt_i32 s20, 4
	ds_read_b32 v0, v0
	s_cselect_b64 s[0:1], -1, 0
	s_add_i32 s2, s95, 0x23eb8
	s_waitcnt lgkmcnt(0)
	v_mov_b32_e32 v0, s2
	s_add_i32 s2, s95, 0x23ebc
	ds_read_b32 v0, v0
	v_mov_b32_e32 v1, s2
	ds_read_b32 v1, v1
	s_add_i32 s2, s95, 0x23ec0
	v_mov_b32_e32 v3, s2
	s_add_i32 s2, s95, 0x23ec4
	s_waitcnt vmcnt(0)
	v_mov_b32_e32 v4, s2
	v_readlane_b32 s2, v252, 35
	v_readlane_b32 s3, v252, 36
	s_lshl_b32 s98, s2, 24
	s_waitcnt lgkmcnt(1)
	v_readfirstlane_b32 s4, v0
	s_mov_b32 s6, s2
	s_lshl_b64 s[2:3], s[98:99], 2
	ds_read_b32 v3, v3
	s_waitcnt lgkmcnt(1)
	v_readfirstlane_b32 s5, v1
	s_add_u32 s4, s4, s2
	ds_read_b32 v4, v4
	s_addc_u32 s5, s5, s3
	s_lshl_b32 s6, s6, 25
	s_add_u32 s10, s86, s6
	s_addc_u32 s11, s87, 0
	s_add_u32 s6, s10, 0x2800000
	s_waitcnt lgkmcnt(1)
	v_readfirstlane_b32 s8, v3
	s_addc_u32 s7, s11, 0
	s_waitcnt lgkmcnt(0)
	v_readfirstlane_b32 s9, v4
	s_add_u32 s8, s8, s2
	s_addc_u32 s9, s9, s3
	s_add_u32 s12, s10, 0x6800000
	s_addc_u32 s13, s11, 0
	s_cmpk_gt_i32 s22, 0x3fff
	s_cselect_b64 s[2:3], -1, 0
	s_or_b64 s[0:1], s[0:1], s[2:3]
	v_lshrrev_b32_e32 v3, 3, v134
	v_lshlrev_b32_e32 v0, 2, v134
	v_lshlrev_b32_e32 v1, 3, v134
	s_mov_b32 s35, s20
	s_and_b64 vcc, exec, s[0:1]
	s_waitcnt vmcnt(4)
	v_and_b32_e32 v72, 28, v0
	s_waitcnt vmcnt(0)
	v_mul_u32_u24_e32 v93, 0x84, v3
	v_or_b32_e32 v73, 8, v3
	v_or_b32_e32 v75, 16, v3
	v_or_b32_e32 v92, 24, v3
	v_and_b32_e32 v74, 56, v1
	v_lshlrev_b32_e32 v94, 2, v3
	s_cbranch_vccnz .LBB0_346
	s_add_i32 s10, s22, 0xffffe000
	s_cmpk_lt_i32 s22, 0x2000
	s_movk_i32 s11, 0x800
	s_cselect_b32 s26, 0x2000, s11
	s_cselect_b32 s18, s11, 0x2000
	s_cselect_b32 s1, s7, s13
	s_cselect_b32 s0, s6, s12
	s_cselect_b32 s3, s5, s9
	s_cselect_b32 s2, s4, s8
	s_cselect_b32 s20, s22, s10
	s_cselect_b32 s16, 13, 11
	s_lshr_b32 s10, s26, 5
	s_abs_i32 s11, s10
	v_cvt_f32_u32_e32 v0, s11
	s_sub_i32 s21, 0, s11
	s_abs_i32 s19, s20
	s_xor_b32 s17, s20, s10
	v_rcp_iflag_f32_e32 v0, v0
	s_ashr_i32 s17, s17, 31
	v_lshlrev_b32_e32 v36, 2, v72
	v_mov_b32_e32 v37, v2
	v_mul_f32_e32 v0, 0x4f7ffffe, v0
	v_cvt_u32_f32_e32 v0, v0
	v_lshlrev_b32_e32 v68, 1, v74
	v_readfirstlane_b32 s24, v0
	s_mul_i32 s21, s21, s24
	s_mul_hi_u32 s21, s24, s21
	s_add_i32 s24, s24, s21
	s_mul_hi_u32 s21, s19, s24
	s_mul_i32 s24, s21, s11
	s_sub_i32 s19, s19, s24
	s_add_i32 s24, s21, 1
	s_sub_i32 s25, s19, s11
	s_cmp_ge_u32 s19, s11
	s_cselect_b32 s21, s24, s21
	s_cselect_b32 s19, s25, s19
	s_add_i32 s24, s21, 1
	s_cmp_ge_u32 s19, s11
	s_cselect_b32 s11, s24, s21
	s_xor_b32 s11, s11, s17
	s_sub_i32 s11, s11, s17
	v_lshl_or_b32 v0, s11, 6, v3
	s_mul_i32 s11, s11, s10
	v_ashrrev_i32_e32 v1, 31, v0
	s_sub_i32 s10, s20, s11
	v_or_b32_e32 v6, 8, v0
	v_or_b32_e32 v8, 16, v0
	v_or_b32_e32 v10, 24, v0
	v_or_b32_e32 v16, 32, v0
	v_or_b32_e32 v18, 40, v0
	v_or_b32_e32 v24, 48, v0
	v_lshlrev_b64 v[4:5], s16, v[0:1]
	s_lshl_b32 s10, s10, 5
	v_ashrrev_i32_e32 v7, 31, v6
	v_ashrrev_i32_e32 v9, 31, v8
	v_ashrrev_i32_e32 v11, 31, v10
	v_ashrrev_i32_e32 v17, 31, v16
	v_ashrrev_i32_e32 v19, 31, v18
	v_ashrrev_i32_e32 v25, 31, v24
	v_or_b32_e32 v0, 56, v0
	s_ashr_i32 s11, s10, 31
	v_lshlrev_b64 v[6:7], s16, v[6:7]
	v_lshlrev_b64 v[8:9], s16, v[8:9]
	v_lshlrev_b64 v[10:11], s16, v[10:11]
	v_lshlrev_b64 v[16:17], s16, v[16:17]
	v_lshlrev_b64 v[18:19], s16, v[18:19]
	v_lshlrev_b64 v[24:25], s16, v[24:25]
	v_ashrrev_i32_e32 v1, 31, v0
	v_lshl_add_u64 v[4:5], v[4:5], 2, s[2:3]
	s_lshl_b64 s[10:11], s[10:11], 2
	v_lshl_add_u64 v[6:7], v[6:7], 2, s[2:3]
	v_lshl_add_u64 v[8:9], v[8:9], 2, s[2:3]
	v_lshl_add_u64 v[10:11], v[10:11], 2, s[2:3]
	v_lshl_add_u64 v[16:17], v[16:17], 2, s[2:3]
	v_lshl_add_u64 v[18:19], v[18:19], 2, s[2:3]
	v_lshl_add_u64 v[24:25], v[24:25], 2, s[2:3]
	v_lshlrev_b64 v[0:1], s16, v[0:1]
	v_lshl_add_u64 v[4:5], v[4:5], 0, s[10:11]
	v_lshl_add_u64 v[6:7], v[6:7], 0, s[10:11]
	v_lshl_add_u64 v[8:9], v[8:9], 0, s[10:11]
	v_lshl_add_u64 v[10:11], v[10:11], 0, s[10:11]
	v_lshl_add_u64 v[16:17], v[16:17], 0, s[10:11]
	v_lshl_add_u64 v[18:19], v[18:19], 0, s[10:11]
	v_lshl_add_u64 v[24:25], v[24:25], 0, s[10:11]
	v_lshl_add_u64 v[0:1], v[0:1], 2, s[2:3]
	v_lshl_add_u64 v[4:5], v[4:5], 0, v[36:37]
	v_lshl_add_u64 v[6:7], v[6:7], 0, v[36:37]
	v_lshl_add_u64 v[8:9], v[8:9], 0, v[36:37]
	v_lshl_add_u64 v[12:13], v[10:11], 0, v[36:37]
	v_lshl_add_u64 v[16:17], v[16:17], 0, v[36:37]
	v_lshl_add_u64 v[20:21], v[18:19], 0, v[36:37]
	v_lshl_add_u64 v[24:25], v[24:25], 0, v[36:37]
	v_lshl_add_u64 v[0:1], v[0:1], 0, s[10:11]
	global_load_dwordx4 v[32:35], v[4:5], off nt
	s_nop 0
	global_load_dwordx4 v[4:7], v[6:7], off nt
	s_nop 0
	global_load_dwordx4 v[8:11], v[8:9], off nt
	s_nop 0
	global_load_dwordx4 v[12:15], v[12:13], off nt
	s_nop 0
	global_load_dwordx4 v[16:19], v[16:17], off nt
	s_nop 0
	global_load_dwordx4 v[20:23], v[20:21], off nt
	v_lshl_add_u64 v[0:1], v[0:1], 0, v[36:37]
	global_load_dwordx4 v[24:27], v[24:25], off nt
	s_nop 0
	global_load_dwordx4 v[28:31], v[0:1], off nt
	v_add_u32_e32 v1, s23, v36
	v_mul_u32_u24_e32 v0, 0x84, v74
	v_add3_u32 v70, s23, v0, v94
	v_lshlrev_b32_e32 v0, 2, v72
	v_add_u32_e32 v71, v1, v93
	s_mov_b32 s19, s22
	s_mov_b32 s25, s20
	s_mov_b32 s21, s26
	s_mov_b32 s24, s18
	s_mov_b64 s[2:3], s[0:1]
	s_waitcnt vmcnt(0)
	s_branch .LBB0_343

; #define LAS __attribute__((address_space(3)))
; #define GAS __attribute__((address_space(1)))
; __device__ __forceinline__ unsigned cvt_pk_bf16(float lo, float hi) { const f32x2 v = {lo, hi}; const bf16x2_t b = __builtin_convertvector(v, bf16x2_t); return __builtin_bit_cast(unsigned, b); }
; #define LDS_WAIT() asm volatile("s_waitcnt lgkmcnt(0)" ::: "memory")
; __device__ __forceinline__ void tr_finish(const TrItem& t, const f32x4 (&v)[8], LAS float* scr, int lane) {
;     const int nblk = t.N / 32, kb = t.item / nblk, nb = t.item % nblk, k0 = 64 * kb, n0 = 32 * nb;
; #pragma unroll
;     for (int i = 0; i < 8; ++i) { const int kk = 8 * i + (lane >> 3); f32x4 x = v[i]; if (t.kscale) x *= t.kscale[k0 + kk];
;         LAS float* d = scr + kk * 33 + 4 * (lane & 7); d[0] = x[0]; d[1] = x[1]; d[2] = x[2]; d[3] = x[3]; }
;     LDS_WAIT();
;     const int c = lane & 7;
; #pragma unroll
;     for (int j = 0; j < 4; ++j) { const int n = (lane >> 3) + 8 * j; const LAS float* sp = scr + (8 * c) * 33 + n;
;         u32x4 o; o.x = cvt_pk_bf16(sp[0 * 33], sp[1 * 33]); o.y = cvt_pk_bf16(sp[2 * 33], sp[3 * 33]); o.z = cvt_pk_bf16(sp[4 * 33], sp[5 * 33]); o.w = cvt_pk_bf16(sp[6 * 33], sp[7 * 33]);
;         *(GAS u32x4*)(t.WT + (size_t)(n0 + n) * t.K + k0 + 8 * c) = o; }
;     LDS_WAIT();
; __device__ __forceinline__ void tr_run(const TrPair& p, LAS float* scr, int first, int stride, int lane) {
;     ...
;     for (int it = first; it < total; it += stride) { const TrItem tc = tn; f32x4 vc[8];
; #pragma unroll
;         for (int i = 0; i < 8; ++i) vc[i] = vn[i];
;         if (it + stride < total) { tn = tr_make(p, it + stride); tr_load(tn, vn, lane); }
;         tr_finish(tc, vc, scr, lane); }
.LBB0_342:
	s_lshr_b32 s17, s26, 5
	v_cvt_f32_u32_e32 v1, s17
	v_add_u32_e32 v69, 0x2200, v71
	v_add_u32_e32 v76, 0x2208, v71
	s_sub_i32 s27, 0, s17
	v_rcp_iflag_f32_e32 v1, v1
	ds_write2_b32 v69, v32, v33 offset1:1
	ds_write2_b32 v76, v34, v35 offset1:1
	s_abs_i32 s26, s20
	s_ashr_i32 s16, s20, 31
	v_mul_f32_e32 v1, 0x4f7ffffe, v1
	v_cvt_u32_f32_e32 v1, v1
	v_mov_b32_e32 v69, v2
	v_readfirstlane_b32 s28, v1
	v_add_u32_e32 v1, 0x2620, v71
	ds_write2_b32 v1, v4, v5 offset1:1
	v_add_u32_e32 v1, 0x2628, v71
	s_mul_i32 s27, s27, s28
	ds_write2_b32 v1, v6, v7 offset1:1
	v_add_u32_e32 v1, 0x2a40, v71
	s_mul_hi_u32 s27, s28, s27
	ds_write2_b32 v1, v8, v9 offset1:1
	v_add_u32_e32 v1, 0x2a48, v71
	s_add_i32 s28, s28, s27
	ds_write2_b32 v1, v10, v11 offset1:1
	v_add_u32_e32 v1, 0x2e60, v71
	s_mul_hi_u32 s27, s26, s28
	ds_write2_b32 v1, v12, v13 offset1:1
	v_add_u32_e32 v1, 0x2e68, v71
	s_mul_i32 s28, s27, s17
	ds_write2_b32 v1, v14, v15 offset1:1
	v_add_u32_e32 v1, 0x3280, v71
	s_sub_i32 s26, s26, s28
	ds_write2_b32 v1, v16, v17 offset1:1
	v_add_u32_e32 v1, 0x3288, v71
	s_add_i32 s29, s27, 1
	s_sub_i32 s28, s26, s17
	ds_write2_b32 v1, v18, v19 offset1:1
	v_add_u32_e32 v1, 0x36a0, v71
	s_cmp_ge_u32 s26, s17
	ds_write2_b32 v1, v20, v21 offset1:1
	v_add_u32_e32 v1, 0x36a8, v71
	s_cselect_b32 s27, s29, s27
	ds_write2_b32 v1, v22, v23 offset1:1
	v_add_u32_e32 v1, 0x3ac0, v71
	s_cselect_b32 s26, s28, s26
	s_add_i32 s28, s27, 1
	ds_write2_b32 v1, v24, v25 offset1:1
	v_add_u32_e32 v1, 0x3ac8, v71
	s_cmp_ge_u32 s26, s17
	ds_write2_b32 v1, v26, v27 offset1:1
	v_add_u32_e32 v1, 0x3ee0, v71
	s_cselect_b32 s26, s28, s27
	ds_write2_b32 v1, v28, v29 offset1:1
	v_add_u32_e32 v1, 0x3ee8, v71
	s_xor_b32 s26, s26, s16
	ds_write2_b32 v1, v30, v31 offset1:1
	s_sub_i32 s26, s26, s16
	s_waitcnt lgkmcnt(0)
	v_add_u32_e32 v1, 0x2000, v70
	s_lshl_b32 s16, s26, 6
	s_mul_i32 s26, s26, s17
	ds_read2_b32 v[8:9], v1 offset0:161 offset1:169
	ds_read2_b32 v[10:11], v1 offset0:128 offset1:136
	ds_read2_b32 v[12:13], v1 offset0:194 offset1:202
	ds_read2_b32 v[14:15], v1 offset0:227 offset1:235
	s_sub_i32 s17, s20, s26
	s_lshl_b32 s20, s17, 5
	s_waitcnt lgkmcnt(2)
	v_cvt_pk_bf16_f32 v4, v10, v8
	v_or_b32_e32 v8, s20, v3
	v_add_u32_e32 v26, 0x2400, v70
	v_mad_u64_u32 v[24:25], s[26:27], v8, s18, 0
	ds_read2_b32 v[16:17], v26 offset0:4 offset1:12
	ds_read2_b32 v[18:19], v26 offset0:37 offset1:45
	ds_read2_b32 v[20:21], v26 offset0:70 offset1:78
	ds_read2_b32 v[22:23], v26 offset0:103 offset1:111
	s_ashr_i32 s26, s20, 31
	s_mul_i32 s28, s26, s18
	s_ashr_i32 s17, s16, 31
	v_add_u32_e32 v25, s28, v25
	v_lshl_add_u64 v[24:25], v[24:25], 1, s[0:1]
	s_lshl_b64 s[16:17], s[16:17], 1
	v_lshl_add_u64 v[24:25], v[24:25], 0, s[16:17]
	s_waitcnt lgkmcnt(4)
	v_cvt_pk_bf16_f32 v5, v12, v14
	s_waitcnt lgkmcnt(2)
	v_cvt_pk_bf16_f32 v6, v16, v18
	s_waitcnt lgkmcnt(0)
	v_cvt_pk_bf16_f32 v7, v20, v22
	v_lshl_add_u64 v[24:25], v[24:25], 0, v[68:69]
	v_or_b32_e32 v8, s20, v73
	global_store_dwordx4 v[24:25], v[4:7], off
	s_andn2_b64 vcc, exec, s[10:11]
	v_cvt_pk_bf16_f32 v4, v11, v9
	v_mad_u64_u32 v[8:9], s[26:27], v8, s18, 0
	v_add_u32_e32 v9, s28, v9
	v_lshl_add_u64 v[8:9], v[8:9], 1, s[0:1]
	v_lshl_add_u64 v[8:9], v[8:9], 0, s[16:17]
	v_cvt_pk_bf16_f32 v5, v13, v15
	v_cvt_pk_bf16_f32 v6, v17, v19
	v_cvt_pk_bf16_f32 v7, v21, v23
	v_lshl_add_u64 v[8:9], v[8:9], 0, v[68:69]
	ds_read2_b32 v[10:11], v1 offset0:144 offset1:152
	ds_read2_b32 v[12:13], v1 offset0:177 offset1:185
	ds_read2_b32 v[14:15], v1 offset0:210 offset1:218
	ds_read2_b32 v[16:17], v1 offset0:243 offset1:251
	ds_read2_b32 v[18:19], v26 offset0:20 offset1:28
	ds_read2_b32 v[20:21], v26 offset0:53 offset1:61
	ds_read2_b32 v[22:23], v26 offset0:86 offset1:94
	ds_read2_b32 v[24:25], v26 offset0:119 offset1:127
	v_or_b32_e32 v1, s20, v75
	global_store_dwordx4 v[8:9], v[4:7], off
	v_mad_u64_u32 v[8:9], s[26:27], v1, s18, 0
	v_add_u32_e32 v9, s28, v9
	v_lshl_add_u64 v[8:9], v[8:9], 1, s[0:1]
	v_lshl_add_u64 v[8:9], v[8:9], 0, s[16:17]
	s_waitcnt lgkmcnt(6)
	v_cvt_pk_bf16_f32 v4, v10, v12
	s_waitcnt lgkmcnt(4)
	v_cvt_pk_bf16_f32 v5, v14, v16
	s_waitcnt lgkmcnt(2)
	v_cvt_pk_bf16_f32 v6, v18, v20
	s_waitcnt lgkmcnt(0)
	v_cvt_pk_bf16_f32 v7, v22, v24
	v_lshl_add_u64 v[8:9], v[8:9], 0, v[68:69]
	v_or_b32_e32 v1, s20, v92
	global_store_dwordx4 v[8:9], v[4:7], off
	v_mad_u64_u32 v[8:9], s[26:27], v1, s18, 0
	v_add_u32_e32 v9, s28, v9
	v_lshl_add_u64 v[8:9], v[8:9], 1, s[0:1]
	v_lshl_add_u64 v[8:9], v[8:9], 0, s[16:17]
	v_cvt_pk_bf16_f32 v4, v11, v13
	v_cvt_pk_bf16_f32 v5, v15, v17
	v_cvt_pk_bf16_f32 v6, v19, v21
	v_cvt_pk_bf16_f32 v7, v23, v25
	v_lshl_add_u64 v[8:9], v[8:9], 0, v[68:69]
	global_store_dwordx4 v[8:9], v[4:7], off
	s_waitcnt lgkmcnt(0)
	s_mov_b32 s20, s25
	s_mov_b32 s26, s21
	s_mov_b32 s18, s24
	s_mov_b64 s[0:1], s[2:3]
	s_waitcnt vmcnt(10)
	v_mov_b32_e32 v32, v52
	v_mov_b32_e32 v33, v53
	v_mov_b32_e32 v34, v54
	v_mov_b32_e32 v35, v55
	v_mov_b32_e32 v4, v36
	v_mov_b32_e32 v5, v37
	v_mov_b32_e32 v6, v38
	v_mov_b32_e32 v7, v39
	s_waitcnt vmcnt(9)
	v_mov_b32_e32 v8, v56
	v_mov_b32_e32 v9, v57
	v_mov_b32_e32 v10, v58
	v_mov_b32_e32 v11, v59
	s_waitcnt vmcnt(8)
	v_mov_b32_e32 v12, v40
	v_mov_b32_e32 v13, v41
	v_mov_b32_e32 v14, v42
	v_mov_b32_e32 v15, v43
	s_waitcnt vmcnt(7)
	v_mov_b32_e32 v16, v60
	v_mov_b32_e32 v17, v61
	v_mov_b32_e32 v18, v62
	v_mov_b32_e32 v19, v63
	s_waitcnt vmcnt(6)
	v_mov_b32_e32 v20, v44
	v_mov_b32_e32 v21, v45
	v_mov_b32_e32 v22, v46
	v_mov_b32_e32 v23, v47
	s_waitcnt vmcnt(5)
	v_mov_b32_e32 v24, v64
	v_mov_b32_e32 v25, v65
	v_mov_b32_e32 v26, v66
	v_mov_b32_e32 v27, v67
	s_waitcnt vmcnt(4)
	v_mov_b32_e32 v28, v48
	v_mov_b32_e32 v29, v49
	v_mov_b32_e32 v30, v50
	v_mov_b32_e32 v31, v51
	s_cbranch_vccz .LBB0_346
.LBB0_343:
	s_add_i32 s19, s19, s94
	s_cmpk_gt_i32 s19, 0x3fff
	s_cselect_b64 s[10:11], -1, 0
	s_and_b64 vcc, exec, s[10:11]
	v_mov_b32_e32 v51, v31
	v_mov_b32_e32 v50, v30
	v_mov_b32_e32 v49, v29
	v_mov_b32_e32 v48, v28
	v_mov_b32_e32 v67, v27
	v_mov_b32_e32 v66, v26
	v_mov_b32_e32 v65, v25
	v_mov_b32_e32 v64, v24
	v_mov_b32_e32 v47, v23
	v_mov_b32_e32 v46, v22
	v_mov_b32_e32 v45, v21
	v_mov_b32_e32 v44, v20
	v_mov_b32_e32 v63, v19
	v_mov_b32_e32 v62, v18
	v_mov_b32_e32 v61, v17
	v_mov_b32_e32 v60, v16
	v_mov_b32_e32 v43, v15
	v_mov_b32_e32 v42, v14
	v_mov_b32_e32 v41, v13
	v_mov_b32_e32 v40, v12
	v_mov_b32_e32 v59, v11
	v_mov_b32_e32 v58, v10
	v_mov_b32_e32 v57, v9
	v_mov_b32_e32 v56, v8
	v_mov_b32_e32 v39, v7
	v_mov_b32_e32 v38, v6
	v_mov_b32_e32 v37, v5
	v_mov_b32_e32 v36, v4
	v_mov_b32_e32 v55, v35
	v_mov_b32_e32 v54, v34
	v_mov_b32_e32 v53, v33
	v_mov_b32_e32 v52, v32
	s_cbranch_vccnz .LBB0_342
	s_movk_i32 s21, 0x2000
	s_movk_i32 s24, 0x800
	s_cmpk_lt_i32 s19, 0x2000
	s_mov_b64 s[2:3], s[6:7]
	s_mov_b64 s[16:17], s[4:5]
	s_mov_b32 s25, s19
	s_cbranch_scc1 .LBB0_341
	s_add_i32 s25, s19, 0xffffe000
	s_movk_i32 s21, 0x800
	s_movk_i32 s24, 0x2000
	s_mov_b64 s[2:3], s[12:13]
	s_mov_b64 s[16:17], s[8:9]
	s_branch .LBB0_341

; #define LAS __attribute__((address_space(3)))
; #define GAS __attribute__((address_space(1)))
; __device__ __forceinline__ void tr_load(const TrItem& t, f32x4 (&v)[8], int lane) {
;     const int nblk = t.N / 32, kb = t.item / nblk, nb = t.item % nblk, k0 = 64 * kb, n0 = 32 * nb;
; #pragma unroll
;     for (int i = 0; i < 8; ++i) v[i] = __builtin_nontemporal_load((const GAS f32x4*)(t.W + (size_t)(k0 + 8 * i + (lane >> 3)) * t.N + n0 + 4 * (lane & 7)));
; }
; __device__ __forceinline__ TrItem tr_make(const TrPair& p, int it) { TrItem t;
;     if (it < p.n0) { t.W = p.W0; t.WT = p.T0; t.kscale = p.s0; t.K = p.K0; t.N = p.N0; t.item = it; }
;     else { t.W = p.W1; t.WT = p.T1; t.kscale = p.s1; t.K = p.K1; t.N = p.N1; t.item = it - p.n0; }
;     return t; }
; __device__ __forceinline__ void tr_run(const TrPair& p, LAS float* scr, int first, int stride, int lane) {
;     const int total = p.n0 + p.n1;
;     f32x4 vn[8]; TrItem tn;
;     if (first < total) { tn = tr_make(p, first); tr_load(tn, vn, lane); }
.LBB0_367:
	s_cmpk_lt_i32 s22, 0x4000
	s_cselect_b64 s[0:1], -1, 0
	s_xor_b64 s[2:3], s[14:15], -1
	s_and_b64 s[0:1], s[2:3], s[0:1]
	s_and_b64 vcc, exec, s[0:1]
	s_cbranch_vccz .LBB0_374
	s_add_i32 s14, s22, 0xffffe000
	s_cmpk_lt_i32 s22, 0x2000
	s_movk_i32 s15, 0x800
	s_cselect_b32 s24, 0x2000, s15
	s_cselect_b32 s18, s15, 0x2000
	s_cselect_b32 s1, s7, s13
	s_cselect_b32 s0, s6, s12
	s_cselect_b32 s3, s5, s9
	s_cselect_b32 s2, s4, s8
	s_cselect_b32 s19, s22, s14
	s_cselect_b32 s16, 13, 11
	s_lshr_b32 s14, s24, 5
	s_abs_i32 s15, s14
	v_cvt_f32_u32_e32 v1, s15
	s_sub_i32 s21, 0, s15
	s_abs_i32 s20, s19
	s_xor_b32 s17, s19, s14
	v_rcp_iflag_f32_e32 v1, v1
	s_ashr_i32 s17, s17, 31
	s_waitcnt vmcnt(0)
	v_lshlrev_b32_e32 v36, 2, v72
	v_mov_b32_e32 v37, v2
	v_mul_f32_e32 v1, 0x4f7ffffe, v1
	v_cvt_u32_f32_e32 v1, v1
	v_lshlrev_b32_e32 v68, 2, v72
	v_lshlrev_b32_e32 v70, 1, v74
	v_readfirstlane_b32 s25, v1
	s_mul_i32 s21, s21, s25
	s_mul_hi_u32 s21, s25, s21
	s_add_i32 s25, s25, s21
	s_mul_hi_u32 s21, s20, s25
	s_mul_i32 s25, s21, s15
	s_sub_i32 s20, s20, s25
	s_add_i32 s25, s21, 1
	s_sub_i32 s26, s20, s15
	s_cmp_ge_u32 s20, s15
	s_cselect_b32 s21, s25, s21
	s_cselect_b32 s20, s26, s20
	s_add_i32 s25, s21, 1
	s_cmp_ge_u32 s20, s15
	s_cselect_b32 s15, s25, s21
	s_xor_b32 s15, s15, s17
	s_sub_i32 s15, s15, s17
	v_lshl_or_b32 v24, s15, 6, v3
	v_ashrrev_i32_e32 v25, 31, v24
	s_mul_i32 s15, s15, s14
	v_lshlrev_b64 v[4:5], s16, v[24:25]
	s_sub_i32 s14, s19, s15
	v_or_b32_e32 v6, 8, v24
	v_or_b32_e32 v8, 16, v24
	v_or_b32_e32 v10, 24, v24
	v_or_b32_e32 v16, 32, v24
	v_or_b32_e32 v18, 40, v24
	v_or_b32_e32 v26, 48, v24
	v_or_b32_e32 v24, 56, v24
	s_lshl_b32 s14, s14, 5
	v_ashrrev_i32_e32 v7, 31, v6
	v_ashrrev_i32_e32 v9, 31, v8
	v_ashrrev_i32_e32 v11, 31, v10
	v_ashrrev_i32_e32 v17, 31, v16
	v_ashrrev_i32_e32 v19, 31, v18
	v_ashrrev_i32_e32 v27, 31, v26
	v_ashrrev_i32_e32 v25, 31, v24
	s_ashr_i32 s15, s14, 31
	v_lshlrev_b64 v[6:7], s16, v[6:7]
	v_lshlrev_b64 v[8:9], s16, v[8:9]
	v_lshlrev_b64 v[10:11], s16, v[10:11]
	v_lshlrev_b64 v[16:17], s16, v[16:17]
	v_lshlrev_b64 v[18:19], s16, v[18:19]
	v_lshlrev_b64 v[26:27], s16, v[26:27]
	v_lshlrev_b64 v[24:25], s16, v[24:25]
	v_lshl_add_u64 v[4:5], v[4:5], 2, s[2:3]
	s_lshl_b64 s[14:15], s[14:15], 2
	v_lshl_add_u64 v[6:7], v[6:7], 2, s[2:3]
	v_lshl_add_u64 v[8:9], v[8:9], 2, s[2:3]
	v_lshl_add_u64 v[10:11], v[10:11], 2, s[2:3]
	v_lshl_add_u64 v[16:17], v[16:17], 2, s[2:3]
	v_lshl_add_u64 v[18:19], v[18:19], 2, s[2:3]
	v_lshl_add_u64 v[26:27], v[26:27], 2, s[2:3]
	v_lshl_add_u64 v[24:25], v[24:25], 2, s[2:3]
	v_lshl_add_u64 v[4:5], v[4:5], 0, s[14:15]
	v_lshl_add_u64 v[6:7], v[6:7], 0, s[14:15]
	v_lshl_add_u64 v[8:9], v[8:9], 0, s[14:15]
	v_lshl_add_u64 v[10:11], v[10:11], 0, s[14:15]
	v_lshl_add_u64 v[16:17], v[16:17], 0, s[14:15]
	v_lshl_add_u64 v[18:19], v[18:19], 0, s[14:15]
	v_lshl_add_u64 v[26:27], v[26:27], 0, s[14:15]
	v_lshl_add_u64 v[24:25], v[24:25], 0, s[14:15]
	v_lshl_add_u64 v[4:5], v[4:5], 0, v[36:37]
	v_lshl_add_u64 v[6:7], v[6:7], 0, v[36:37]
	v_lshl_add_u64 v[8:9], v[8:9], 0, v[36:37]
	v_lshl_add_u64 v[12:13], v[10:11], 0, v[36:37]
	v_lshl_add_u64 v[16:17], v[16:17], 0, v[36:37]
	v_lshl_add_u64 v[20:21], v[18:19], 0, v[36:37]
	v_lshl_add_u64 v[26:27], v[26:27], 0, v[36:37]
	v_lshl_add_u64 v[28:29], v[24:25], 0, v[36:37]
	global_load_dwordx4 v[32:35], v[4:5], off nt
	s_nop 0
	global_load_dwordx4 v[4:7], v[6:7], off nt
	s_nop 0
	global_load_dwordx4 v[8:11], v[8:9], off nt
	s_nop 0
	global_load_dwordx4 v[12:15], v[12:13], off nt
	s_nop 0
	global_load_dwordx4 v[16:19], v[16:17], off nt
	s_nop 0
	global_load_dwordx4 v[20:23], v[20:21], off nt
	s_nop 0
	global_load_dwordx4 v[24:27], v[26:27], off nt
	s_nop 0
	global_load_dwordx4 v[28:31], v[28:29], off nt
	v_add_u32_e32 v36, s23, v36
	v_mul_u32_u24_e32 v1, 0x84, v74
	v_add3_u32 v1, s23, v1, v94
	v_add_u32_e32 v72, v36, v93
	s_mov_b32 s23, s19
	s_mov_b32 s20, s24
	s_mov_b32 s21, s18
	s_mov_b64 s[2:3], s[0:1]
	s_waitcnt vmcnt(0)
	s_branch .LBB0_371

; #define LAS __attribute__((address_space(3)))
; #define GAS __attribute__((address_space(1)))
; __device__ __forceinline__ unsigned cvt_pk_bf16(float lo, float hi) { const f32x2 v = {lo, hi}; const bf16x2_t b = __builtin_convertvector(v, bf16x2_t); return __builtin_bit_cast(unsigned, b); }
; #define LDS_WAIT() asm volatile("s_waitcnt lgkmcnt(0)" ::: "memory")
; __device__ __forceinline__ void tr_finish(const TrItem& t, const f32x4 (&v)[8], LAS float* scr, int lane) {
;     const int nblk = t.N / 32, kb = t.item / nblk, nb = t.item % nblk, k0 = 64 * kb, n0 = 32 * nb;
; #pragma unroll
;     for (int i = 0; i < 8; ++i) { const int kk = 8 * i + (lane >> 3); f32x4 x = v[i]; if (t.kscale) x *= t.kscale[k0 + kk];
;         LAS float* d = scr + kk * 33 + 4 * (lane & 7); d[0] = x[0]; d[1] = x[1]; d[2] = x[2]; d[3] = x[3]; }
;     LDS_WAIT();
;     const int c = lane & 7;
; #pragma unroll
;     for (int j = 0; j < 4; ++j) { const int n = (lane >> 3) + 8 * j; const LAS float* sp = scr + (8 * c) * 33 + n;
;         u32x4 o; o.x = cvt_pk_bf16(sp[0 * 33], sp[1 * 33]); o.y = cvt_pk_bf16(sp[2 * 33], sp[3 * 33]); o.z = cvt_pk_bf16(sp[4 * 33], sp[5 * 33]); o.w = cvt_pk_bf16(sp[6 * 33], sp[7 * 33]);
;         *(GAS u32x4*)(t.WT + (size_t)(n0 + n) * t.K + k0 + 8 * c) = o; }
;     LDS_WAIT();
; __device__ __forceinline__ void tr_run(const TrPair& p, LAS float* scr, int first, int stride, int lane) {
;     ...
;     for (int it = first; it < total; it += stride) { const TrItem tc = tn; f32x4 vc[8];
; #pragma unroll
;         for (int i = 0; i < 8; ++i) vc[i] = vn[i];
;         if (it + stride < total) { tn = tr_make(p, it + stride); tr_load(tn, vn, lane); }
;         tr_finish(tc, vc, scr, lane); }
.LBB0_370:
	s_lshr_b32 s17, s24, 5
	v_cvt_f32_u32_e32 v69, s17
	v_add_u32_e32 v71, 0x2200, v72
	v_add_u32_e32 v74, 0x2208, v72
	ds_write2_b32 v71, v32, v33 offset1:1
	ds_write2_b32 v74, v34, v35 offset1:1
	v_rcp_iflag_f32_e32 v69, v69
	v_add_u32_e32 v32, 0x2620, v72
	s_sub_i32 s25, 0, s17
	ds_write2_b32 v32, v4, v5 offset1:1
	v_mul_f32_e32 v69, 0x4f7ffffe, v69
	v_cvt_u32_f32_e32 v69, v69
	v_add_u32_e32 v4, 0x2628, v72
	ds_write2_b32 v4, v6, v7 offset1:1
	v_add_u32_e32 v4, 0x2a40, v72
	v_readfirstlane_b32 s26, v69
	s_mul_i32 s25, s25, s26
	s_mul_hi_u32 s25, s26, s25
	ds_write2_b32 v4, v8, v9 offset1:1
	v_add_u32_e32 v4, 0x2a48, v72
	s_abs_i32 s24, s19
	s_add_i32 s26, s26, s25
	ds_write2_b32 v4, v10, v11 offset1:1
	v_add_u32_e32 v4, 0x2e60, v72
	s_mul_hi_u32 s25, s24, s26
	ds_write2_b32 v4, v12, v13 offset1:1
	v_add_u32_e32 v4, 0x2e68, v72
	s_mul_i32 s26, s25, s17
	ds_write2_b32 v4, v14, v15 offset1:1
	v_add_u32_e32 v4, 0x3280, v72
	s_sub_i32 s24, s24, s26
	ds_write2_b32 v4, v16, v17 offset1:1
	v_add_u32_e32 v4, 0x3288, v72
	s_ashr_i32 s16, s19, 31
	s_add_i32 s27, s25, 1
	s_sub_i32 s26, s24, s17
	ds_write2_b32 v4, v18, v19 offset1:1
	v_add_u32_e32 v4, 0x36a0, v72
	s_cmp_ge_u32 s24, s17
	ds_write2_b32 v4, v20, v21 offset1:1
	v_add_u32_e32 v4, 0x36a8, v72
	s_cselect_b32 s25, s27, s25
	ds_write2_b32 v4, v22, v23 offset1:1
	v_add_u32_e32 v4, 0x3ac0, v72
	s_cselect_b32 s24, s26, s24
	s_add_i32 s26, s25, 1
	ds_write2_b32 v4, v24, v25 offset1:1
	v_add_u32_e32 v4, 0x3ac8, v72
	s_cmp_ge_u32 s24, s17
	ds_write2_b32 v4, v26, v27 offset1:1
	v_add_u32_e32 v4, 0x3ee0, v72
	s_cselect_b32 s24, s26, s25
	ds_write2_b32 v4, v28, v29 offset1:1
	v_add_u32_e32 v4, 0x3ee8, v72
	s_xor_b32 s24, s24, s16
	ds_write2_b32 v4, v30, v31 offset1:1
	s_sub_i32 s24, s24, s16
	s_waitcnt lgkmcnt(0)
	v_add_u32_e32 v26, 0x2000, v1
	s_lshl_b32 s16, s24, 6
	s_mul_i32 s24, s24, s17
	ds_read2_b32 v[8:9], v26 offset0:161 offset1:169
	ds_read2_b32 v[10:11], v26 offset0:128 offset1:136
	ds_read2_b32 v[12:13], v26 offset0:194 offset1:202
	ds_read2_b32 v[14:15], v26 offset0:227 offset1:235
	s_sub_i32 s17, s19, s24
	s_lshl_b32 s19, s17, 5
	s_waitcnt lgkmcnt(0)
	v_cvt_pk_bf16_f32 v4, v10, v8
	v_or_b32_e32 v8, s19, v3
	v_add_u32_e32 v27, 0x2400, v1
	v_mad_u64_u32 v[24:25], s[24:25], v8, s18, 0
	ds_read2_b32 v[16:17], v27 offset0:4 offset1:12
	ds_read2_b32 v[18:19], v27 offset0:37 offset1:45
	ds_read2_b32 v[20:21], v27 offset0:70 offset1:78
	ds_read2_b32 v[22:23], v27 offset0:103 offset1:111
	s_ashr_i32 s24, s19, 31
	s_mul_i32 s26, s24, s18
	s_ashr_i32 s17, s16, 31
	v_add_u32_e32 v25, s26, v25
	v_lshl_add_u64 v[24:25], v[24:25], 1, s[0:1]
	s_lshl_b64 s[16:17], s[16:17], 1
	v_lshl_add_u64 v[24:25], v[24:25], 0, s[16:17]
	v_mov_b32_e32 v71, v2
	v_cvt_pk_bf16_f32 v5, v12, v14
	s_waitcnt lgkmcnt(2)
	v_cvt_pk_bf16_f32 v6, v16, v18
	s_waitcnt lgkmcnt(0)
	v_cvt_pk_bf16_f32 v7, v20, v22
	v_lshl_add_u64 v[24:25], v[24:25], 0, v[70:71]
	v_or_b32_e32 v8, s19, v73
	global_store_dwordx4 v[24:25], v[4:7], off
	s_andn2_b64 vcc, exec, s[14:15]
	v_cvt_pk_bf16_f32 v4, v11, v9
	v_mad_u64_u32 v[8:9], s[24:25], v8, s18, 0
	v_add_u32_e32 v9, s26, v9
	v_lshl_add_u64 v[8:9], v[8:9], 1, s[0:1]
	v_lshl_add_u64 v[8:9], v[8:9], 0, s[16:17]
	v_cvt_pk_bf16_f32 v5, v13, v15
	v_cvt_pk_bf16_f32 v6, v17, v19
	v_cvt_pk_bf16_f32 v7, v21, v23
	v_lshl_add_u64 v[8:9], v[8:9], 0, v[70:71]
	ds_read2_b32 v[10:11], v26 offset0:144 offset1:152
	ds_read2_b32 v[12:13], v26 offset0:177 offset1:185
	ds_read2_b32 v[14:15], v26 offset0:210 offset1:218
	ds_read2_b32 v[16:17], v26 offset0:243 offset1:251
	ds_read2_b32 v[18:19], v27 offset0:20 offset1:28
	ds_read2_b32 v[20:21], v27 offset0:53 offset1:61
	ds_read2_b32 v[22:23], v27 offset0:86 offset1:94
	ds_read2_b32 v[24:25], v27 offset0:119 offset1:127
	global_store_dwordx4 v[8:9], v[4:7], off
	v_or_b32_e32 v8, s19, v75
	v_mad_u64_u32 v[8:9], s[24:25], v8, s18, 0
	v_add_u32_e32 v9, s26, v9
	v_lshl_add_u64 v[8:9], v[8:9], 1, s[0:1]
	v_lshl_add_u64 v[8:9], v[8:9], 0, s[16:17]
	s_waitcnt lgkmcnt(6)
	v_cvt_pk_bf16_f32 v4, v10, v12
	s_waitcnt lgkmcnt(4)
	v_cvt_pk_bf16_f32 v5, v14, v16
	s_waitcnt lgkmcnt(2)
	v_cvt_pk_bf16_f32 v6, v18, v20
	s_waitcnt lgkmcnt(0)
	v_cvt_pk_bf16_f32 v7, v22, v24
	v_lshl_add_u64 v[8:9], v[8:9], 0, v[70:71]
	global_store_dwordx4 v[8:9], v[4:7], off
	v_or_b32_e32 v8, s19, v92
	v_mad_u64_u32 v[8:9], s[18:19], v8, s18, 0
	v_add_u32_e32 v9, s26, v9
	v_lshl_add_u64 v[8:9], v[8:9], 1, s[0:1]
	v_lshl_add_u64 v[8:9], v[8:9], 0, s[16:17]
	v_cvt_pk_bf16_f32 v4, v11, v13
	v_cvt_pk_bf16_f32 v5, v15, v17
	v_cvt_pk_bf16_f32 v6, v19, v21
	v_cvt_pk_bf16_f32 v7, v23, v25
	v_lshl_add_u64 v[8:9], v[8:9], 0, v[70:71]
	global_store_dwordx4 v[8:9], v[4:7], off
	s_waitcnt lgkmcnt(0)
	s_mov_b32 s19, s23
	s_mov_b32 s24, s20
	s_mov_b32 s18, s21
	s_mov_b64 s[0:1], s[2:3]
	s_waitcnt vmcnt(10)
	v_mov_b32_e32 v32, v52
	v_mov_b32_e32 v33, v53
	v_mov_b32_e32 v34, v54
	v_mov_b32_e32 v35, v55
	v_mov_b32_e32 v4, v36
	v_mov_b32_e32 v5, v37
	v_mov_b32_e32 v6, v38
	v_mov_b32_e32 v7, v39
	s_waitcnt vmcnt(9)
	v_mov_b32_e32 v8, v56
	v_mov_b32_e32 v9, v57
	v_mov_b32_e32 v10, v58
	v_mov_b32_e32 v11, v59
	s_waitcnt vmcnt(8)
	v_mov_b32_e32 v12, v40
	v_mov_b32_e32 v13, v41
	v_mov_b32_e32 v14, v42
	v_mov_b32_e32 v15, v43
	s_waitcnt vmcnt(7)
	v_mov_b32_e32 v16, v60
	v_mov_b32_e32 v17, v61
	v_mov_b32_e32 v18, v62
	v_mov_b32_e32 v19, v63
	s_waitcnt vmcnt(6)
	v_mov_b32_e32 v20, v44
	v_mov_b32_e32 v21, v45
	v_mov_b32_e32 v22, v46
	v_mov_b32_e32 v23, v47
	s_waitcnt vmcnt(5)
	v_mov_b32_e32 v24, v64
	v_mov_b32_e32 v25, v65
	v_mov_b32_e32 v26, v66
	v_mov_b32_e32 v27, v67
	s_waitcnt vmcnt(4)
	v_mov_b32_e32 v28, v48
	v_mov_b32_e32 v29, v49
	v_mov_b32_e32 v30, v50
	v_mov_b32_e32 v31, v51
	s_cbranch_vccz .LBB0_374
.LBB0_371:
	s_add_i32 s22, s22, s94
	s_cmpk_gt_i32 s22, 0x3fff
	s_cselect_b64 s[14:15], -1, 0
	s_and_b64 vcc, exec, s[14:15]
	v_mov_b32_e32 v51, v31
	v_mov_b32_e32 v50, v30
	v_mov_b32_e32 v49, v29
	v_mov_b32_e32 v48, v28
	v_mov_b32_e32 v67, v27
	v_mov_b32_e32 v66, v26
	v_mov_b32_e32 v65, v25
	v_mov_b32_e32 v64, v24
	v_mov_b32_e32 v47, v23
	v_mov_b32_e32 v46, v22
	v_mov_b32_e32 v45, v21
	v_mov_b32_e32 v44, v20
	v_mov_b32_e32 v63, v19
	v_mov_b32_e32 v62, v18
	v_mov_b32_e32 v61, v17
	v_mov_b32_e32 v60, v16
	v_mov_b32_e32 v43, v15
	v_mov_b32_e32 v42, v14
	v_mov_b32_e32 v41, v13
	v_mov_b32_e32 v40, v12
	v_mov_b32_e32 v59, v11
	v_mov_b32_e32 v58, v10
	v_mov_b32_e32 v57, v9
	v_mov_b32_e32 v56, v8
	v_mov_b32_e32 v39, v7
	v_mov_b32_e32 v38, v6
	v_mov_b32_e32 v37, v5
	v_mov_b32_e32 v36, v4
	v_mov_b32_e32 v55, v35
	v_mov_b32_e32 v54, v34
	v_mov_b32_e32 v53, v33
	v_mov_b32_e32 v52, v32
	s_cbranch_vccnz .LBB0_370
	s_movk_i32 s20, 0x2000
	s_movk_i32 s21, 0x800
	s_cmpk_lt_i32 s22, 0x2000
	s_mov_b64 s[2:3], s[6:7]
	s_mov_b64 s[16:17], s[4:5]
	s_mov_b32 s23, s22
	s_cbranch_scc1 .LBB0_369
	s_add_i32 s23, s22, 0xffffe000
	s_movk_i32 s20, 0x800
	s_movk_i32 s21, 0x2000
	s_mov_b64 s[2:3], s[12:13]
	s_mov_b64 s[16:17], s[8:9]
	s_branch .LBB0_369
